# v10 + attention: next item's global loads issued before the LDS-staging barrier instead of after it
# baseline (speedup 1.0000x reference)
; __device__ __forceinline__ void attn_phase(int wv, const Args& a, LAS unsigned char* lds, int w, bool dmy) {
;     ...
;         AT_WRITEBLK(sl);
;         bf16x8 qc[4];
; #pragma unroll
;         for (int k4 = 0; k4 < 4; ++k4) qc[k4] = qf[k4];
;         const float qscale = rsqrtf(qs * (1.f / 128.f) + EPS) * 0.08838834764831845f;
.LBB0_655:
	s_waitcnt vmcnt(14)
	v_fmamk_f32 v32, v120, 0x3c000000, v226
	v_mul_f32_e32 v33, 0x4b800000, v32
	v_cmp_gt_f32_e32 vcc, s33, v32
	v_lshlrev_b32_e32 v34, 16, v1
	v_and_b32_e32 v35, 0xffff0000, v1
	v_cndmask_b32_e32 v32, v32, v33, vcc
	v_rsq_f32_e32 v32, v32
	v_lshlrev_b32_e32 v38, 16, v3
	v_and_b32_e32 v39, 0xffff0000, v3
	s_and_b32 s2, s0, 1
	v_mul_f32_e32 v33, 0x45800000, v32
	v_cndmask_b32_e32 v36, v32, v33, vcc
	v_lshlrev_b32_e32 v32, 16, v0
	v_and_b32_e32 v33, 0xffff0000, v0
	v_pk_mul_f32 v[32:33], v[36:37], v[32:33] op_sel_hi:[0,1]
	v_pk_mul_f32 v[34:35], v[36:37], v[34:35] op_sel_hi:[0,1]
	v_cvt_pk_bf16_f32 v32, v32, v33
	v_cvt_pk_bf16_f32 v33, v34, v35
	v_lshlrev_b32_e32 v34, 16, v2
	v_and_b32_e32 v35, 0xffff0000, v2
	v_pk_mul_f32 v[34:35], v[36:37], v[34:35] op_sel_hi:[0,1]
	v_pk_mul_f32 v[36:37], v[36:37], v[38:39] op_sel_hi:[0,1]
	v_cvt_pk_bf16_f32 v34, v34, v35
	v_cvt_pk_bf16_f32 v35, v36, v37
	s_waitcnt vmcnt(12)
	v_fmamk_f32 v36, v121, 0x3c000000, v226
	v_mul_f32_e32 v37, 0x4b800000, v36
	v_cmp_gt_f32_e32 vcc, s33, v36
	s_lshl_b32 s3, s2, 7
	v_add_u32_e32 v40, s3, v89
	v_cndmask_b32_e32 v36, v36, v37, vcc
	v_rsq_f32_e32 v38, v36
	v_mad_u64_u32 v[36:37], s[6:7], v40, s11, v[94:95]
	ds_write_b128 v36, v[32:35]
	v_mul_f32_e32 v32, 0x45800000, v38
	v_cndmask_b32_e32 v38, v38, v32, vcc
	v_lshlrev_b32_e32 v32, 16, v4
	v_and_b32_e32 v33, 0xffff0000, v4
	v_lshlrev_b32_e32 v34, 16, v5
	v_and_b32_e32 v35, 0xffff0000, v5
	v_pk_mul_f32 v[32:33], v[38:39], v[32:33] op_sel_hi:[0,1]
	v_pk_mul_f32 v[34:35], v[38:39], v[34:35] op_sel_hi:[0,1]
	v_cvt_pk_bf16_f32 v32, v32, v33
	v_cvt_pk_bf16_f32 v33, v34, v35
	v_lshlrev_b32_e32 v34, 16, v6
	v_and_b32_e32 v35, 0xffff0000, v6
	v_pk_mul_f32 v[34:35], v[38:39], v[34:35] op_sel_hi:[0,1]
	v_cvt_pk_bf16_f32 v34, v34, v35
	s_waitcnt vmcnt(10)
	v_fmamk_f32 v35, v122, 0x3c000000, v226
	v_mul_f32_e32 v37, 0x4b800000, v35
	v_cmp_gt_f32_e32 vcc, s33, v35
	v_lshlrev_b32_e32 v40, 16, v7
	v_and_b32_e32 v41, 0xffff0000, v7
	v_cndmask_b32_e32 v35, v35, v37, vcc
	v_rsq_f32_e32 v37, v35
	v_pk_mul_f32 v[38:39], v[38:39], v[40:41] op_sel_hi:[0,1]
	v_cvt_pk_bf16_f32 v35, v38, v39
	ds_write_b128 v36, v[32:35] offset:8704
	v_mul_f32_e32 v32, 0x45800000, v37
	v_cndmask_b32_e32 v38, v37, v32, vcc
	s_waitcnt vmcnt(9)
	v_lshlrev_b32_e32 v32, 16, v16
	v_and_b32_e32 v33, 0xffff0000, v16
	v_lshlrev_b32_e32 v34, 16, v17
	v_and_b32_e32 v35, 0xffff0000, v17
	v_pk_mul_f32 v[32:33], v[38:39], v[32:33] op_sel_hi:[0,1]
	v_pk_mul_f32 v[34:35], v[38:39], v[34:35] op_sel_hi:[0,1]
	v_cvt_pk_bf16_f32 v32, v32, v33
	v_cvt_pk_bf16_f32 v33, v34, v35
	v_lshlrev_b32_e32 v34, 16, v18
	v_and_b32_e32 v35, 0xffff0000, v18
	v_pk_mul_f32 v[34:35], v[38:39], v[34:35] op_sel_hi:[0,1]
	v_cvt_pk_bf16_f32 v34, v34, v35
	s_waitcnt vmcnt(6)
	v_fmamk_f32 v35, v123, 0x3c000000, v226
	v_mul_f32_e32 v37, 0x4b800000, v35
	v_cmp_gt_f32_e32 vcc, s33, v35
	v_lshlrev_b32_e32 v40, 16, v19
	v_and_b32_e32 v41, 0xffff0000, v19
	v_cndmask_b32_e32 v35, v35, v37, vcc
	v_rsq_f32_e32 v37, v35
	v_pk_mul_f32 v[38:39], v[38:39], v[40:41] op_sel_hi:[0,1]
	v_cvt_pk_bf16_f32 v35, v38, v39
	ds_write_b128 v36, v[32:35] offset:17408
	v_mul_f32_e32 v32, 0x45800000, v37
	v_cndmask_b32_e32 v38, v37, v32, vcc
	v_lshlrev_b32_e32 v32, 16, v20
	v_and_b32_e32 v33, 0xffff0000, v20
	v_lshlrev_b32_e32 v34, 16, v21
	v_and_b32_e32 v35, 0xffff0000, v21
	v_pk_mul_f32 v[32:33], v[38:39], v[32:33] op_sel_hi:[0,1]
	v_pk_mul_f32 v[34:35], v[38:39], v[34:35] op_sel_hi:[0,1]
	v_cvt_pk_bf16_f32 v32, v32, v33
	v_cvt_pk_bf16_f32 v33, v34, v35
	v_lshlrev_b32_e32 v34, 16, v22
	v_and_b32_e32 v35, 0xffff0000, v22
	v_lshlrev_b32_e32 v40, 16, v23
	v_and_b32_e32 v41, 0xffff0000, v23
	v_pk_mul_f32 v[34:35], v[38:39], v[34:35] op_sel_hi:[0,1]
	v_pk_mul_f32 v[38:39], v[38:39], v[40:41] op_sel_hi:[0,1]
	v_cvt_pk_bf16_f32 v34, v34, v35
	v_cvt_pk_bf16_f32 v35, v38, v39
	ds_write_b128 v36, v[32:35] offset:26112
	v_or_b32_e32 v32, s3, v84
	v_add_u32_e32 v32, v32, v105
	v_lshl_add_u32 v32, v32, 1, 0
	v_lshlrev_b32_e32 v33, 16, v12
	s_mov_b32 s3, 0xffff
	v_lshrrev_b32_e32 v34, 16, v8
	s_mov_b32 s5, 0xffff0000
	v_add_u32_e32 v32, 0x11000, v32
	v_and_or_b32 v33, v8, s3, v33
	v_and_or_b32 v34, v12, s5, v34
	ds_write2_b32 v32, v33, v34 offset1:132
	v_lshlrev_b32_e32 v33, 16, v13
	v_lshrrev_b32_e32 v34, 16, v9
	v_and_or_b32 v33, v9, s3, v33
	v_and_or_b32 v34, v13, s5, v34
	v_add_u32_e32 v35, 0x400, v32
	ds_write2_b32 v35, v33, v34 offset0:8 offset1:140
	v_lshlrev_b32_e32 v33, 16, v14
	v_lshrrev_b32_e32 v34, 16, v10
	v_and_or_b32 v33, v10, s3, v33
	v_and_or_b32 v34, v14, s5, v34
	v_add_u32_e32 v35, 0x800, v32
	ds_write2_b32 v35, v33, v34 offset0:16 offset1:148
	v_lshlrev_b32_e32 v33, 16, v15
	v_lshrrev_b32_e32 v34, 16, v11
	v_and_or_b32 v33, v11, s3, v33
	v_and_or_b32 v34, v15, s5, v34
	v_add_u32_e32 v35, 0xc00, v32
	ds_write2_b32 v35, v33, v34 offset0:24 offset1:156
	s_waitcnt vmcnt(5)
	v_lshlrev_b32_e32 v33, 16, v28
	v_lshrrev_b32_e32 v34, 16, v24
	v_and_or_b32 v33, v24, s3, v33
	v_and_or_b32 v34, v28, s5, v34
	v_add_u32_e32 v35, 0x8400, v32
	ds_write2_b32 v35, v33, v34 offset1:132
	v_lshlrev_b32_e32 v33, 16, v29
	v_lshrrev_b32_e32 v34, 16, v25
	v_and_or_b32 v33, v25, s3, v33
	v_and_or_b32 v34, v29, s5, v34
	v_add_u32_e32 v35, 0x8800, v32
	ds_write2_b32 v35, v33, v34 offset0:8 offset1:140
	v_lshlrev_b32_e32 v33, 16, v30
	v_lshrrev_b32_e32 v34, 16, v26
	v_and_or_b32 v33, v26, s3, v33
	v_and_or_b32 v34, v30, s5, v34
	v_add_u32_e32 v35, 0x8c00, v32
	ds_write2_b32 v35, v33, v34 offset0:16 offset1:148
	v_lshlrev_b32_e32 v33, 16, v31
	v_lshrrev_b32_e32 v34, 16, v27
	v_and_or_b32 v33, v27, s3, v33
	v_and_or_b32 v34, v31, s5, v34
	v_add_u32_e32 v32, 0x9000, v32
	ds_write2_b32 v32, v33, v34 offset0:24 offset1:156
	s_waitcnt vmcnt(0)
	v_fmamk_f32 v32, v99, 0x3c000000, v226
	v_mul_f32_e32 v33, 0x4b800000, v32
	v_cmp_gt_f32_e32 vcc, s33, v32
	v_mov_b64_e32 v[44:45], v[48:49]
	v_mov_b64_e32 v[40:41], v[52:53]
	v_cndmask_b32_e32 v64, v32, v33, vcc
	v_mov_b64_e32 v[36:37], v[56:57]
	v_mov_b64_e32 v[32:33], v[60:61]
	s_mov_b32 s8, s81
	s_cmp_eq_u32 s4, 11
	v_mov_b64_e32 v[46:47], v[50:51]
	v_mov_b64_e32 v[42:43], v[54:55]
	v_mov_b64_e32 v[38:39], v[58:59]
	v_mov_b64_e32 v[34:35], v[62:63]
	s_mov_b32 s5, s0
	s_mov_b32 s83, s1
	s_mov_b32 s82, s80
	s_mov_b64 s[84:85], s[86:87]
	s_cbranch_scc1 .LBB0_657
; #define LAS __attribute__((address_space(3)))
; __device__ __forceinline__ int opaque_tid(int wv) { int l; asm volatile("v_mbcnt_lo_u32_b32 %0, -1, 0\n\tv_mbcnt_hi_u32_b32 %0, -1, %0" : "=v"(l)); return (wv << 6) | l; }
; __device__ __forceinline__ void attn_phase(int wv, const Args& a, LAS unsigned char* lds, int w, bool dmy) {
;     const int tid = opaque_tid(wv), lane = tid & 63, wid = __builtin_amdgcn_readfirstlane(tid >> 6), fr = lane & 15, fq = lane >> 4;
;     bf16_t* AQ = (bf16_t*)(a.ws + WS_AQ); const bf16_t* AK = (const bf16_t*)(a.ws + WS_AK); const bf16_t* AV = (const bf16_t*)(a.ws + WS_AV);
;     const float* HS = (const float*)(a.ws + WS_HSSQ); float* LSE = (float*)(a.ws + WS_LSE);
;     const int krow = tid >> 4, kc = tid & 15;
;     const int vc = tid >> 6, vrow = (tid & 63) * 2;
;     const int qi = 16 * wid + fr;
;     u32x4 kr[4], vr[4]; float rk[4]; bf16x8 qf[4]; float qs;
	v_readlane_b32 s3, v253, 8
	s_add_i32 s3, s3, s4
	s_and_b32 s5, s3, 63
	s_bfe_u32 s7, s3, 0x20006
	s_ashr_i32 s3, s3, 8
	s_mul_hi_i32 s6, s3, 0x55555556
	s_lshr_b32 s81, s6, 31
	s_add_i32 s6, s6, s81
	s_mul_i32 s81, s6, 3
	s_sub_i32 s3, s3, s81
	s_lshl_b32 s81, s3, 1
	s_lshr_b32 s82, 64, s81
	s_sub_i32 s83, 6, s81
	s_add_i32 s82, s82, -1
	s_lshr_b32 s83, s5, s83
	s_and_b32 s5, s82, s5
	s_lshl_b32 s3, s3, 2
	s_or_b32 s82, s3, s7
	s_ashr_i32 s7, s6, 31
	s_lshl_b32 s3, s5, 7
	s_lshl_b64 s[84:85], s[6:7], 13
	v_add_u32_e32 v16, s3, v89
	s_lshl_b32 s6, s82, 7
	s_ashr_i32 s7, s6, 31
	v_ashrrev_i32_e32 v17, 31, v16
	s_or_b32 s84, s84, s83
	s_lshl_b64 s[88:89], s[6:7], 1
	v_lshlrev_b64 v[0:1], s81, v[16:17]
	v_lshl_add_u64 v[18:19], v[86:87], 0, s[88:89]
	v_lshl_add_u64 v[0:1], v[0:1], 0, s[84:85]
	s_movk_i32 s10, 0xc00
	v_mad_u64_u32 v[2:3], s[90:91], v0, s10, v[18:19]
	v_mov_b32_e32 v4, v3
	v_mad_u64_u32 v[4:5], s[90:91], v1, s10, v[4:5]
	v_readlane_b32 s90, v253, 42
	v_readlane_b32 s91, v253, 43
	s_movk_i32 s9, 0x60
	v_mov_b32_e32 v3, v4
	v_mov_b64_e32 v[44:45], s[90:91]
	v_mad_u64_u32 v[4:5], s[90:91], v0, s9, v[44:45]
	s_ashr_i32 s83, s82, 31
	v_readlane_b32 s6, v253, 40
	v_mov_b32_e32 v0, v5
	s_add_u32 s6, s6, s88
	v_readlane_b32 s7, v253, 41
	v_mad_u64_u32 v[0:1], s[90:91], v1, s9, v[0:1]
	v_or_b32_e32 v188, s3, v84
	s_addc_u32 s7, s7, s89
	v_mov_b32_e32 v5, v0
	v_lshlrev_b64 v[0:1], s81, v[188:189]
	v_lshl_add_u64 v[0:1], v[0:1], 0, s[84:85]
	v_mov_b64_e32 v[12:13], s[6:7]
	v_mad_u64_u32 v[20:21], s[6:7], v0, s10, v[12:13]
	v_mov_b32_e32 v0, v21
	v_mad_u64_u32 v[0:1], s[6:7], v1, s10, v[0:1]
	v_mov_b32_e32 v21, v0
	v_add_u32_e32 v0, 32, v16
	v_ashrrev_i32_e32 v1, 31, v0
	v_lshlrev_b64 v[0:1], s81, v[0:1]
	s_lshl_b64 s[90:91], s[82:83], 2
	v_lshl_add_u64 v[14:15], v[0:1], 0, s[84:85]
	v_lshl_add_u64 v[8:9], v[4:5], 0, s[90:91]
	v_mad_u64_u32 v[4:5], s[6:7], v14, s10, v[18:19]
	v_mad_u64_u32 v[22:23], s[6:7], v14, s9, v[44:45]
	v_mov_b32_e32 v0, v5
	v_mov_b32_e32 v14, v23
	v_mad_u64_u32 v[0:1], s[6:7], v15, s10, v[0:1]
	v_mad_u64_u32 v[14:15], s[6:7], v15, s9, v[14:15]
	v_mov_b32_e32 v23, v14
	v_lshl_add_u64 v[10:11], v[20:21], 0, v[90:91]
	v_mov_b32_e32 v5, v0
	v_lshl_add_u64 v[14:15], v[22:23], 0, s[90:91]
	v_or_b32_e32 v188, 1, v188
	global_load_dwordx4 v[0:3], v[2:3], off
	s_nop 0
	global_load_dwordx4 v[4:7], v[4:5], off
	s_nop 0
	global_load_dword v120, v[8:9], off offset:48
	s_nop 0
	global_load_dwordx4 v[8:11], v[10:11], off
	s_nop 0
	global_load_dword v121, v[14:15], off offset:48
	v_lshlrev_b64 v[14:15], s81, v[188:189]
	v_lshl_add_u64 v[14:15], v[14:15], 0, s[84:85]
	v_mad_u64_u32 v[28:29], s[6:7], v14, s10, v[12:13]
	v_mov_b32_e32 v12, v29
	v_add_u32_e32 v14, 64, v16
	v_mad_u64_u32 v[12:13], s[6:7], v15, s10, v[12:13]
	v_ashrrev_i32_e32 v15, 31, v14
	v_lshlrev_b64 v[14:15], s81, v[14:15]
	v_lshl_add_u64 v[14:15], v[14:15], 0, s[84:85]
	v_mad_u64_u32 v[22:23], s[6:7], v14, s10, v[18:19]
	v_mov_b32_e32 v24, v23
	v_mad_u64_u32 v[24:25], s[6:7], v15, s10, v[24:25]
	v_mov_b32_e32 v23, v24
	v_mad_u64_u32 v[24:25], s[6:7], v14, s9, v[44:45]
	v_mov_b32_e32 v14, v25
	v_add_u32_e32 v16, 0x60, v16
	v_mad_u64_u32 v[14:15], s[6:7], v15, s9, v[14:15]
	v_ashrrev_i32_e32 v17, 31, v16
	v_mov_b32_e32 v29, v12
	v_mov_b32_e32 v25, v14
	v_lshlrev_b64 v[16:17], s81, v[16:17]
	v_lshl_add_u64 v[12:13], v[28:29], 0, v[90:91]
	v_lshl_add_u64 v[24:25], v[24:25], 0, s[90:91]
	v_lshl_add_u64 v[26:27], v[16:17], 0, s[84:85]
	global_load_dwordx4 v[12:15], v[12:13], off
	s_nop 0
	global_load_dword v122, v[24:25], off offset:48
	v_lshl_add_u64 v[24:25], v[20:21], 0, v[92:93]
	v_mad_u64_u32 v[20:21], s[6:7], v26, s10, v[18:19]
	v_mad_u64_u32 v[30:31], s[6:7], v26, s9, v[44:45]
	v_mov_b32_e32 v16, v21
	v_mov_b32_e32 v26, v31
	v_mad_u64_u32 v[16:17], s[6:7], v27, s10, v[16:17]
	v_mad_u64_u32 v[26:27], s[6:7], v27, s9, v[26:27]
	v_mov_b32_e32 v31, v26
	v_mov_b32_e32 v21, v16
	v_lshl_add_u64 v[30:31], v[30:31], 0, s[90:91]
	global_load_dwordx4 v[16:19], v[22:23], off
	s_nop 0
	global_load_dwordx4 v[20:23], v[20:21], off
	s_nop 0
	global_load_dwordx4 v[24:27], v[24:25], off
	s_nop 0
	global_load_dword v123, v[30:31], off offset:48
	v_add_u32_e32 v30, s3, v95
	v_ashrrev_i32_e32 v31, 31, v30
	v_lshlrev_b64 v[30:31], s81, v[30:31]
	v_lshl_add_u64 v[46:47], v[30:31], 0, s[84:85]
	v_mov_b64_e32 v[30:31], s[78:79]
	v_mad_u64_u32 v[30:31], s[6:7], v46, s10, v[30:31]
	v_mov_b32_e32 v32, v31
	v_mad_u64_u32 v[32:33], s[6:7], v47, s10, v[32:33]
	v_mov_b32_e32 v31, v32
	v_mad_u64_u32 v[44:45], s[6:7], v46, s9, v[44:45]
	v_lshl_add_u64 v[28:29], v[28:29], 0, v[92:93]
	v_lshl_add_u64 v[30:31], v[30:31], 0, s[88:89]
	v_mov_b32_e32 v99, v189
	v_mov_b32_e32 v46, v45
	v_lshl_add_u64 v[66:67], v[30:31], 0, v[98:99]
	global_load_dwordx4 v[28:31], v[28:29], off
	s_nop 0
	global_load_dwordx4 v[32:35], v[66:67], off
	global_load_dwordx4 v[36:39], v[66:67], off offset:64
	global_load_dwordx4 v[40:43], v[66:67], off offset:128
	v_mad_u64_u32 v[46:47], s[6:7], v47, s9, v[46:47]
	v_mov_b32_e32 v45, v46
	v_lshl_add_u64 v[68:69], v[44:45], 0, s[90:91]
	global_load_dwordx4 v[44:47], v[66:67], off offset:192
	global_load_dword v99, v[68:69], off
	s_lshl_b32 s83, 1, s81
; __device__ __forceinline__ f32x4 mfma16(bf16x8 a, bf16x8 b, f32x4 c) { return __builtin_amdgcn_mfma_f32_16x16x32_bf16(a, b, c, 0, 0, 0); }
; #define AT_LOADQ(T) do { const size_t tq_ = (T).tb + (size_t)(128 * (T).n + qi) * (T).d; \
;         _Pragma("unroll") for (int k4_ = 0; k4_ < 4; ++k4_) qf[k4_] = *(const bf16x8*)(AQ + tq_ * ATW + (T).head * 128 + k4_ * 32 + 8 * fq); qs = HS[tq_ * 24 + (T).head]; } while (0)
; __device__ __forceinline__ void attn_phase(int wv, const Args& a, LAS unsigned char* lds, int w, bool dmy) {
;     ...
;         const float qscale = rsqrtf(qs * (1.f / 128.f) + EPS) * 0.08838834764831845f;
;         const size_t tokq = T.tb + (size_t)(128 * n + qi) * T.d;
;         __syncthreads();
;         if (it < 11) { T = attn_decode(12 * w + it + 1);
;             AT_LOADBLK(T, T.n); AT_LOADQ(T); }
;         const int px = (sl ^ 1) << 3;
;         const int lo2 = (wid & ~1) < 6 ? (wid & ~1) : 6;
;         f32x4 sT[10];
;         float mx = -INFINITY;
; #pragma unroll
;         for (int i = 0; i < 10; ++i) {
;             const int kt = lo2 + i, pkt = kt ^ px;
;             f32x4 ac = (f32x4){0.f, 0.f, 0.f, 0.f};
; #pragma unroll
;             for (int k4 = 0; k4 < 4; ++k4) ac = mfma16(lds_ld16(lds + AT_K + ((pkt * 16 + fr) * 136 + k4 * 32 + 8 * fq) * 2), qc[k4], ac);
.LBB0_657:
	s_waitcnt lgkmcnt(0)
	s_barrier
	v_rsq_f32_e32 v64, v64
	v_mov_b64_e32 v[66:67], s[86:87]
	v_lshl_add_u32 v65, s0, 7, v95
	v_mad_u64_u32 v[102:103], s[6:7], v65, s1, v[66:67]
	v_ashrrev_i32_e32 v68, 31, v65
	v_mov_b32_e32 v66, v103
	v_mad_u64_u32 v[100:101], s[6:7], v68, s1, v[66:67]
	v_mul_f32_e32 v65, 0x45800000, v64
	v_readfirstlane_b32 s3, v95
	v_cndmask_b32_e32 v64, v64, v65, vcc
	s_lshr_b32 s3, s3, 4
	s_lshl_b32 s1, s2, 3
	s_xor_b32 s1, s1, 8
	s_add_u32 s1, s1, s3
	s_movk_i32 s9, 0x110
	v_mad_u32_u24 v83, v85, s9, v96
	v_add_u32_e32 v82, v106, v88
	v_lshl_add_u32 v82, v82, 1, s94
	v_sub_u32_e32 v80, v88, v85
	v_mul_f32_e32 v64, 0x3db504f3, v64
	s_add_u32 s6, s1, 0
	s_and_b32 s6, s6, 15
	s_mul_i32 s7, s6, 0x1100
	s_lshl_b32 s6, s6, 5
	v_add_u32_e32 v68, s7, v83
	v_add_u32_e32 v182, s6, v82
	s_add_u32 s6, s1, 1
	s_and_b32 s6, s6, 15
	s_mul_i32 s7, s6, 0x1100
	s_lshl_b32 s6, s6, 5
	v_add_u32_e32 v69, s7, v83
	v_add_u32_e32 v183, s6, v82
	s_add_u32 s6, s1, 2
	s_and_b32 s6, s6, 15
	s_mul_i32 s7, s6, 0x1100
	s_lshl_b32 s6, s6, 5
	v_add_u32_e32 v70, s7, v83
	v_add_u32_e32 v184, s6, v82
	s_add_u32 s6, s1, 3
	s_and_b32 s6, s6, 15
	s_mul_i32 s7, s6, 0x1100
	s_lshl_b32 s6, s6, 5
	v_add_u32_e32 v71, s7, v83
	v_add_u32_e32 v185, s6, v82
	s_add_u32 s6, s1, 4
	s_and_b32 s6, s6, 15
	s_mul_i32 s7, s6, 0x1100
	s_lshl_b32 s6, s6, 5
	v_add_u32_e32 v72, s7, v83
	v_add_u32_e32 v186, s6, v82
	s_add_u32 s6, s1, 5
	s_and_b32 s6, s6, 15
	s_mul_i32 s7, s6, 0x1100
	s_lshl_b32 s6, s6, 5
	v_add_u32_e32 v73, s7, v83
	v_add_u32_e32 v187, s6, v82
	s_add_u32 s6, s1, 6
	s_and_b32 s6, s6, 15
	s_mul_i32 s7, s6, 0x1100
	s_lshl_b32 s6, s6, 5
	v_add_u32_e32 v74, s7, v83
	v_add_u32_e32 v227, s6, v82
	s_add_u32 s6, s1, 7
	s_and_b32 s6, s6, 15
	s_mul_i32 s7, s6, 0x1100
	s_lshl_b32 s6, s6, 5
	v_add_u32_e32 v75, s7, v83
	v_add_u32_e32 v228, s6, v82
	s_add_u32 s6, s1, 8
	s_and_b32 s6, s6, 15
	s_mul_i32 s7, s6, 0x1100
	s_lshl_b32 s6, s6, 5
	v_add_u32_e32 v76, s7, v83
	v_add_u32_e32 v234, s6, v82
	ds_read_b128 v[166:169], v68
	ds_read_b128 v[170:173], v68 offset:64
	ds_read_b128 v[174:177], v68 offset:128
	ds_read_b128 v[178:181], v68 offset:192
	ds_read_b128 v[198:201], v69
	ds_read_b128 v[202:205], v69 offset:64
	ds_read_b128 v[206:209], v69 offset:128
	ds_read_b128 v[210:213], v69 offset:192
	s_waitcnt lgkmcnt(7)
	v_mfma_f32_16x16x32_bf16 v[124:127], v[166:169], v[60:63], 0
	s_waitcnt lgkmcnt(6)
	v_mfma_f32_16x16x32_bf16 v[124:127], v[170:173], v[56:59], v[124:127]
	s_waitcnt lgkmcnt(5)
	v_mfma_f32_16x16x32_bf16 v[124:127], v[174:177], v[52:55], v[124:127]
	s_waitcnt lgkmcnt(4)
	v_mfma_f32_16x16x32_bf16 v[124:127], v[178:181], v[48:51], v[124:127]
	ds_read_b128 v[166:169], v70
	ds_read_b128 v[170:173], v70 offset:64
	ds_read_b128 v[174:177], v70 offset:128
	ds_read_b128 v[178:181], v70 offset:192
	s_waitcnt lgkmcnt(7)
	v_mfma_f32_16x16x32_bf16 v[128:131], v[198:201], v[60:63], 0
	s_waitcnt lgkmcnt(6)
	v_mfma_f32_16x16x32_bf16 v[128:131], v[202:205], v[56:59], v[128:131]
	s_waitcnt lgkmcnt(5)
	v_mfma_f32_16x16x32_bf16 v[128:131], v[206:209], v[52:55], v[128:131]
	s_waitcnt lgkmcnt(4)
	v_mfma_f32_16x16x32_bf16 v[128:131], v[210:213], v[48:51], v[128:131]
	ds_read_b128 v[198:201], v71
	ds_read_b128 v[202:205], v71 offset:64
	ds_read_b128 v[206:209], v71 offset:128
	ds_read_b128 v[210:213], v71 offset:192
	s_waitcnt lgkmcnt(7)
	v_mfma_f32_16x16x32_bf16 v[132:135], v[166:169], v[60:63], 0
	s_waitcnt lgkmcnt(6)
	v_mfma_f32_16x16x32_bf16 v[132:135], v[170:173], v[56:59], v[132:135]
	s_waitcnt lgkmcnt(5)
	v_mfma_f32_16x16x32_bf16 v[132:135], v[174:177], v[52:55], v[132:135]
	s_waitcnt lgkmcnt(4)
	v_mfma_f32_16x16x32_bf16 v[132:135], v[178:181], v[48:51], v[132:135]
	ds_read_b128 v[166:169], v72
	ds_read_b128 v[170:173], v72 offset:64
	ds_read_b128 v[174:177], v72 offset:128
	ds_read_b128 v[178:181], v72 offset:192
	s_waitcnt lgkmcnt(7)
	v_mfma_f32_16x16x32_bf16 v[136:139], v[198:201], v[60:63], 0
	s_waitcnt lgkmcnt(6)
	v_mfma_f32_16x16x32_bf16 v[136:139], v[202:205], v[56:59], v[136:139]
	s_waitcnt lgkmcnt(5)
	v_mfma_f32_16x16x32_bf16 v[136:139], v[206:209], v[52:55], v[136:139]
	s_waitcnt lgkmcnt(4)
	v_mfma_f32_16x16x32_bf16 v[136:139], v[210:213], v[48:51], v[136:139]
	ds_read_b128 v[198:201], v73
	ds_read_b128 v[202:205], v73 offset:64
	ds_read_b128 v[206:209], v73 offset:128
	ds_read_b128 v[210:213], v73 offset:192
	s_waitcnt lgkmcnt(7)
; __device__ __forceinline__ f32x4 mfma16(bf16x8 a, bf16x8 b, f32x4 c) { return __builtin_amdgcn_mfma_f32_16x16x32_bf16(a, b, c, 0, 0, 0); }
; __device__ __forceinline__ void attn_phase(int wv, const Args& a, LAS unsigned char* lds, int w, bool dmy) {
;     ...
;         for (int i = 0; i < 10; ++i) {
;             const int kt = lo2 + i, pkt = kt ^ px;
;             f32x4 ac = (f32x4){0.f, 0.f, 0.f, 0.f};
; #pragma unroll
;             for (int k4 = 0; k4 < 4; ++k4) ac = mfma16(lds_ld16(lds + AT_K + ((pkt * 16 + fr) * 136 + k4 * 32 + 8 * fq) * 2), qc[k4], ac);
; #pragma unroll
;             for (int rr = 0; rr < 4; ++rr) {
;                 const int ki = kt * 16 + 4 * fq + rr;
;                 const bool valid = (ki >= qi) && (ki <= qi + 128) && (n > 0 || ki >= 128);
;                 const float sv = valid ? ac[rr] * qscale : -INFINITY;
;                 ac[rr] = sv; mx = fmaxf(mx, sv);
;             }
;             sT[i] = ac;
;         }
	v_mfma_f32_16x16x32_bf16 v[140:143], v[166:169], v[60:63], 0
	s_waitcnt lgkmcnt(6)
	v_mfma_f32_16x16x32_bf16 v[140:143], v[170:173], v[56:59], v[140:143]
	s_waitcnt lgkmcnt(5)
	v_mfma_f32_16x16x32_bf16 v[140:143], v[174:177], v[52:55], v[140:143]
	s_waitcnt lgkmcnt(4)
	v_mfma_f32_16x16x32_bf16 v[140:143], v[178:181], v[48:51], v[140:143]
	ds_read_b128 v[166:169], v74
	ds_read_b128 v[170:173], v74 offset:64
	ds_read_b128 v[174:177], v74 offset:128
	ds_read_b128 v[178:181], v74 offset:192
	s_waitcnt lgkmcnt(7)
	v_mfma_f32_16x16x32_bf16 v[144:147], v[198:201], v[60:63], 0
	s_waitcnt lgkmcnt(6)
	v_mfma_f32_16x16x32_bf16 v[144:147], v[202:205], v[56:59], v[144:147]
	s_waitcnt lgkmcnt(5)
	v_mfma_f32_16x16x32_bf16 v[144:147], v[206:209], v[52:55], v[144:147]
	s_waitcnt lgkmcnt(4)
	v_mfma_f32_16x16x32_bf16 v[144:147], v[210:213], v[48:51], v[144:147]
	ds_read_b128 v[198:201], v75
	ds_read_b128 v[202:205], v75 offset:64
	ds_read_b128 v[206:209], v75 offset:128
	ds_read_b128 v[210:213], v75 offset:192
	s_waitcnt lgkmcnt(7)
	v_mfma_f32_16x16x32_bf16 v[148:151], v[166:169], v[60:63], 0
	s_waitcnt lgkmcnt(6)
	v_mfma_f32_16x16x32_bf16 v[148:151], v[170:173], v[56:59], v[148:151]
	s_waitcnt lgkmcnt(5)
	v_mfma_f32_16x16x32_bf16 v[148:151], v[174:177], v[52:55], v[148:151]
	s_waitcnt lgkmcnt(4)
	v_mfma_f32_16x16x32_bf16 v[148:151], v[178:181], v[48:51], v[148:151]
	ds_read_b128 v[166:169], v76
	ds_read_b128 v[170:173], v76 offset:64
	ds_read_b128 v[174:177], v76 offset:128
	ds_read_b128 v[178:181], v76 offset:192
	s_waitcnt lgkmcnt(7)
	v_mfma_f32_16x16x32_bf16 v[152:155], v[198:201], v[60:63], 0
	s_waitcnt lgkmcnt(6)
	v_mfma_f32_16x16x32_bf16 v[152:155], v[202:205], v[56:59], v[152:155]
	s_waitcnt lgkmcnt(5)
	v_mfma_f32_16x16x32_bf16 v[152:155], v[206:209], v[52:55], v[152:155]
	s_waitcnt lgkmcnt(4)
	v_mfma_f32_16x16x32_bf16 v[152:155], v[210:213], v[48:51], v[152:155]
	s_waitcnt lgkmcnt(3)
	v_mfma_f32_16x16x32_bf16 v[156:159], v[166:169], v[60:63], 0
	s_waitcnt lgkmcnt(2)
	v_mfma_f32_16x16x32_bf16 v[156:159], v[170:173], v[56:59], v[156:159]
	s_waitcnt lgkmcnt(1)
	v_mfma_f32_16x16x32_bf16 v[156:159], v[174:177], v[52:55], v[156:159]
	s_waitcnt lgkmcnt(0)
	v_mfma_f32_16x16x32_bf16 v[156:159], v[178:181], v[48:51], v[156:159]
	v_mov_b32_e32 v66, v64
	v_mul_f32_e32 v64, 0x3fb8aa3b, v64
	v_cmp_le_i32_e64 s[88:89], 0, v80
	v_cmp_le_i32_e64 s[90:91], -1, v80
	v_cmp_le_i32_e64 s[2:3], -2, v80
	v_cmp_le_i32_e64 s[6:7], -3, v80
	v_cndmask_b32_e64 v124, v238, v124, s[88:89]
	v_cndmask_b32_e64 v125, v238, v125, s[90:91]
	v_cndmask_b32_e64 v126, v238, v126, s[2:3]
	v_cndmask_b32_e64 v127, v238, v127, s[6:7]
	v_cmp_ge_i32_e64 s[88:89], 0, v80
	v_cmp_ge_i32_e64 s[90:91], -1, v80
	v_cmp_ge_i32_e64 s[2:3], -2, v80
	v_cmp_ge_i32_e64 s[6:7], -3, v80
	s_nop 3
	v_cndmask_b32_e64 v156, v238, v156, s[88:89]
	v_cndmask_b32_e64 v157, v238, v157, s[90:91]
	v_cndmask_b32_e64 v158, v238, v158, s[2:3]
	v_cndmask_b32_e64 v159, v238, v159, s[6:7]
	s_cmp_lg_u32 s0, 0
	s_cbranch_scc1 .Lat_n_ok
	v_readfirstlane_b32 s3, v95
	s_lshr_b32 s3, s3, 4
	s_add_u32 s6, s3, 0
	s_cmp_lt_u32 s6, 8
	s_cbranch_scc0 .Lat_n_ok
	v_mov_b32_e32 v124, v238
	v_mov_b32_e32 v125, v238
	v_mov_b32_e32 v126, v238
	v_mov_b32_e32 v127, v238
	s_add_u32 s6, s3, 1
	s_cmp_lt_u32 s6, 8
	s_cbranch_scc0 .Lat_n_ok
	v_mov_b32_e32 v128, v238
	v_mov_b32_e32 v129, v238
	v_mov_b32_e32 v130, v238
	v_mov_b32_e32 v131, v238
	s_add_u32 s6, s3, 2
	s_cmp_lt_u32 s6, 8
	s_cbranch_scc0 .Lat_n_ok
	v_mov_b32_e32 v132, v238
	v_mov_b32_e32 v133, v238
	v_mov_b32_e32 v134, v238
	v_mov_b32_e32 v135, v238
	s_add_u32 s6, s3, 3
	s_cmp_lt_u32 s6, 8
	s_cbranch_scc0 .Lat_n_ok
	v_mov_b32_e32 v136, v238
	v_mov_b32_e32 v137, v238
	v_mov_b32_e32 v138, v238
	v_mov_b32_e32 v139, v238
	s_add_u32 s6, s3, 4
	s_cmp_lt_u32 s6, 8
	s_cbranch_scc0 .Lat_n_ok
	v_mov_b32_e32 v140, v238
	v_mov_b32_e32 v141, v238
	v_mov_b32_e32 v142, v238
	v_mov_b32_e32 v143, v238
	s_add_u32 s6, s3, 5
	s_cmp_lt_u32 s6, 8
	s_cbranch_scc0 .Lat_n_ok
	v_mov_b32_e32 v144, v238
	v_mov_b32_e32 v145, v238
	v_mov_b32_e32 v146, v238
	v_mov_b32_e32 v147, v238
	s_add_u32 s6, s3, 6
	s_cmp_lt_u32 s6, 8
	s_cbranch_scc0 .Lat_n_ok
	v_mov_b32_e32 v148, v238
	v_mov_b32_e32 v149, v238
	v_mov_b32_e32 v150, v238
	v_mov_b32_e32 v151, v238
	s_add_u32 s6, s3, 7
	s_cmp_lt_u32 s6, 8
	s_cbranch_scc0 .Lat_n_ok
	v_mov_b32_e32 v152, v238
	v_mov_b32_e32 v153, v238
	v_mov_b32_e32 v154, v238
	v_mov_b32_e32 v155, v238
